# global attention epilogue: 8 dwordx2 row-per-lane stores -> 4 dwordx4 via v_permlane32_swap
# speedup vs baseline: 1.0102x; 1.0015x over previous
; DI void attn_item(const Params& p, int layer, int item, char* smem) {
;     ...
;   float l_tot = lacc[0];
;   if (hasSink) l_tot += __builtin_amdgcn_exp2f(sinkv * LOG2E - m_fix);
;   float inv = 1.f / l_tot;
;   int T = (mode == 3) ? (TLAT + b * 256 + (qpos - 4096)) : (b * 4096 + qpos);
;   u16* od = p.O + (size_t)T * LDK + head16 * 64;
; #pragma unroll
;   for (int g = 0; g < 4; ++g) {
;     int d0 = 8 * g + 4 * h;
;     *(uint2*)(od + d0) = make_uint2(pack_bf16(o0[4 * g] * inv, o0[4 * g + 1] * inv), pack_bf16(o0[4 * g + 2] * inv, o0[4 * g + 3] * inv));
;     *(uint2*)(od + 32 + d0) = make_uint2(pack_bf16(o1[4 * g] * inv, o1[4 * g + 1] * inv), pack_bf16(o1[4 * g + 2] * inv, o1[4 * g + 3] * inv));
;   }
.LBB0_267:
	s_nop 5
	v_add_f32_e32 v51, v51, v52
	s_nop 0
	v_mov_b32_e32 v52, v51
	s_nop 1
	v_permlane32_swap_b32_e32 v51, v52
	s_nop 1
	v_add_f32_e32 v50, v50, v51
	v_add_f32_e32 v50, v50, v52
	v_div_scale_f32 v0, s[0:1], v50, v50, 1.0
	v_rcp_f32_e32 v3, v0
	v_lshl_add_u32 v2, s5, 12, v134
	s_lshl_b32 s0, s4, 6
	s_ashr_i32 s1, s0, 31
	v_fma_f32 v4, -v0, v3, 1.0
	v_fmac_f32_e32 v3, v4, v3
	v_div_scale_f32 v4, vcc, 1.0, v50, 1.0
	v_mul_f32_e32 v5, v4, v3
	v_fma_f32 v6, -v0, v5, v4
	v_fmac_f32_e32 v5, v6, v3
	v_fma_f32 v0, -v0, v5, v4
	v_div_fmas_f32 v0, v0, v3, v5
	v_ashrrev_i32_e32 v3, 31, v2
	v_lshlrev_b64 v[2:3], 11, v[2:3]
	v_div_fixup_f32 v4, v0, v50, 1.0
	v_lshl_add_u64 v[2:3], s[90:91], 0, v[2:3]
	v_lshl_add_u64 v[2:3], s[0:1], 1, v[2:3]
	v_lshlrev_b32_e32 v0, 4, v140
	v_lshl_add_u64 v[2:3], v[2:3], 0, v[0:1]
	v_pk_mul_f32 v[6:7], v[34:35], v[4:5] op_sel_hi:[1,0]
	v_pk_mul_f32 v[8:9], v[36:37], v[4:5] op_sel_hi:[1,0]
	v_pk_mul_f32 v[10:11], v[38:39], v[4:5] op_sel_hi:[1,0]
	v_pk_mul_f32 v[12:13], v[40:41], v[4:5] op_sel_hi:[1,0]
	v_cvt_pk_bf16_f32 v6, v6, v7
	v_cvt_pk_bf16_f32 v7, v8, v9
	v_cvt_pk_bf16_f32 v8, v10, v11
	v_cvt_pk_bf16_f32 v9, v12, v13
	s_nop 1
	v_permlane32_swap_b32_e32 v6, v8
	v_permlane32_swap_b32_e32 v7, v9
	global_store_dwordx4 v[2:3], v[6:9], off offset:1280
	v_pk_mul_f32 v[14:15], v[42:43], v[4:5] op_sel_hi:[1,0]
	v_pk_mul_f32 v[16:17], v[44:45], v[4:5] op_sel_hi:[1,0]
	v_pk_mul_f32 v[10:11], v[46:47], v[4:5] op_sel_hi:[1,0]
	v_pk_mul_f32 v[12:13], v[48:49], v[4:5] op_sel_hi:[1,0]
	v_cvt_pk_bf16_f32 v14, v14, v15
	v_cvt_pk_bf16_f32 v15, v16, v17
	v_cvt_pk_bf16_f32 v16, v10, v11
	v_cvt_pk_bf16_f32 v17, v12, v13
	s_nop 1
	v_permlane32_swap_b32_e32 v14, v16
	v_permlane32_swap_b32_e32 v15, v17
	global_store_dwordx4 v[2:3], v[14:17], off offset:1312
	v_pk_mul_f32 v[6:7], v[18:19], v[4:5] op_sel_hi:[1,0]
	v_pk_mul_f32 v[8:9], v[20:21], v[4:5] op_sel_hi:[1,0]
	v_pk_mul_f32 v[10:11], v[22:23], v[4:5] op_sel_hi:[1,0]
	v_pk_mul_f32 v[12:13], v[24:25], v[4:5] op_sel_hi:[1,0]
	v_cvt_pk_bf16_f32 v6, v6, v7
	v_cvt_pk_bf16_f32 v7, v8, v9
	v_cvt_pk_bf16_f32 v8, v10, v11
	v_cvt_pk_bf16_f32 v9, v12, v13
	s_nop 1
	v_permlane32_swap_b32_e32 v6, v8
	v_permlane32_swap_b32_e32 v7, v9
	global_store_dwordx4 v[2:3], v[6:9], off offset:1344
	v_pk_mul_f32 v[14:15], v[26:27], v[4:5] op_sel_hi:[1,0]
	v_pk_mul_f32 v[16:17], v[28:29], v[4:5] op_sel_hi:[1,0]
	v_pk_mul_f32 v[10:11], v[30:31], v[4:5] op_sel_hi:[1,0]
	v_pk_mul_f32 v[12:13], v[32:33], v[4:5] op_sel_hi:[1,0]
	v_cvt_pk_bf16_f32 v14, v14, v15
	v_cvt_pk_bf16_f32 v15, v16, v17
	v_cvt_pk_bf16_f32 v16, v10, v11
	v_cvt_pk_bf16_f32 v17, v12, v13
	s_nop 1
	v_permlane32_swap_b32_e32 v14, v16
	v_permlane32_swap_b32_e32 v15, v17
	global_store_dwordx4 v[2:3], v[14:17], off offset:1376
	s_and_saveexec_b64 s[0:1], s[68:69]
	s_cbranch_execz .LBB0_236
	s_branch .LBB0_498
